# attention sub-head-1 epilogue: the 16 serialized 16-byte re-reads of the o0 block issued as 9 loads together into dead VGPRs, later reads become copies
# speedup vs baseline: 1.0235x; 1.0015x over previous
.LBB0_977:
	v_add_f32_e32 v3, v96, v97
	v_add_f32_e32 v3, v98, v3
	v_add_f32_e32 v3, v99, v3
	v_add_f32_e32 v3, v100, v3
	v_add_f32_e32 v3, v101, v3
	v_add_f32_e32 v3, v102, v3
	v_add_f32_e32 v3, v103, v3
	v_add_f32_e32 v3, v104, v3
	v_add_f32_e32 v3, v105, v3
	v_add_f32_e32 v3, v106, v3
	v_add_f32_e32 v3, v107, v3
	v_add_f32_e32 v3, v108, v3
	v_add_f32_e32 v3, v109, v3
	v_add_f32_e32 v3, v110, v3
	v_add_f32_e32 v3, v111, v3
	v_add_f32_e32 v3, v3, v80
	v_add_f32_e32 v3, v81, v3
	v_add_f32_e32 v3, v82, v3
	v_add_f32_e32 v3, v83, v3
	v_add_f32_e32 v3, v84, v3
	v_add_f32_e32 v3, v85, v3
	v_add_f32_e32 v3, v86, v3
	v_add_f32_e32 v3, v87, v3
	v_add_f32_e32 v3, v88, v3
	v_add_f32_e32 v3, v89, v3
	v_add_f32_e32 v3, v90, v3
	v_add_f32_e32 v3, v91, v3
	v_add_f32_e32 v3, v92, v3
	v_add_f32_e32 v3, v93, v3
	v_add_f32_e32 v3, v94, v3
	v_add_f32_e32 v3, v95, v3
	v_add_f32_e32 v0, v0, v3
	v_cvt_pk_bf16_f32 v4, v96, v97
	v_cvt_pk_bf16_f32 v5, v98, v99
	v_cvt_pk_bf16_f32 v6, v100, v101
	v_cvt_pk_bf16_f32 v7, v102, v103
	v_cvt_pk_bf16_f32 v8, v104, v105
	v_cvt_pk_bf16_f32 v9, v106, v107
	v_cvt_pk_bf16_f32 v10, v108, v109
	v_cvt_pk_bf16_f32 v11, v110, v111
	v_cvt_pk_bf16_f32 v12, v80, v81
	v_cvt_pk_bf16_f32 v13, v82, v83
	v_cvt_pk_bf16_f32 v14, v84, v85
	v_cvt_pk_bf16_f32 v15, v86, v87
	v_cvt_pk_bf16_f32 v80, v88, v89
	v_cvt_pk_bf16_f32 v81, v90, v91
	v_cvt_pk_bf16_f32 v82, v92, v93
	v_cvt_pk_bf16_f32 v83, v94, v95
	v_lshl_add_u32 v3, s90, 1, v246
	ds_read_b64_tr_b16 v[84:85],v3 offset:0
	ds_read_b64_tr_b16 v[86:87],v3 offset:512
	ds_read_b64_tr_b16 v[88:89],v3 offset:1024
	ds_read_b64_tr_b16 v[90:91],v3 offset:1536
	ds_read_b64_tr_b16 v[92:93],v3 offset:2048
	ds_read_b64_tr_b16 v[94:95],v3 offset:2560
	ds_read_b64_tr_b16 v[96:97],v3 offset:3072
	ds_read_b64_tr_b16 v[98:99],v3 offset:3584
	s_waitcnt lgkmcnt(0)
	s_nop 0
	v_mfma_f32_32x32x16_bf16 v[64:79], v[4:7], v[84:87], v[64:79]
	ds_read_b64_tr_b16 v[84:85],v3 offset:4096
	ds_read_b64_tr_b16 v[86:87],v3 offset:4608
	v_mfma_f32_32x32x16_bf16 v[64:79], v[8:11], v[88:91], v[64:79]
	ds_read_b64_tr_b16 v[88:89],v3 offset:5120
	ds_read_b64_tr_b16 v[90:91],v3 offset:5632
	v_mfma_f32_32x32x16_bf16 v[64:79], v[12:15], v[92:95], v[64:79]
	ds_read_b64_tr_b16 v[92:93],v3 offset:6144
	ds_read_b64_tr_b16 v[94:95],v3 offset:6656
	ds_read_b64_tr_b16 v[100:101],v3 offset:7168
	ds_read_b64_tr_b16 v[102:103],v3 offset:7680
	s_waitcnt lgkmcnt(0)
	v_mfma_f32_32x32x16_bf16 v[64:79], v[80:83], v[96:99], v[64:79]
	v_mfma_f32_32x32x16_bf16 v[48:63], v[4:7], v[84:87], v[48:63]
	ds_read_b64_tr_b16 v[84:85],v3 offset:8192
	ds_read_b64_tr_b16 v[86:87],v3 offset:8704
	v_mfma_f32_32x32x16_bf16 v[48:63], v[8:11], v[88:91], v[48:63]
	ds_read_b64_tr_b16 v[88:89],v3 offset:9216
	ds_read_b64_tr_b16 v[90:91],v3 offset:9728
	v_mfma_f32_32x32x16_bf16 v[48:63], v[12:15], v[92:95], v[48:63]
	ds_read_b64_tr_b16 v[92:93],v3 offset:10240
	ds_read_b64_tr_b16 v[94:95],v3 offset:10752
	ds_read_b64_tr_b16 v[96:97],v3 offset:11264
	ds_read_b64_tr_b16 v[98:99],v3 offset:11776
	s_waitcnt lgkmcnt(0)
	v_mfma_f32_32x32x16_bf16 v[48:63], v[80:83], v[100:103], v[48:63]
	v_mfma_f32_32x32x16_bf16 v[32:47], v[4:7], v[84:87], v[32:47]
	ds_read_b64_tr_b16 v[84:85],v3 offset:12288
	ds_read_b64_tr_b16 v[86:87],v3 offset:12800
	v_mfma_f32_32x32x16_bf16 v[32:47], v[8:11], v[88:91], v[32:47]
	ds_read_b64_tr_b16 v[88:89],v3 offset:13312
	ds_read_b64_tr_b16 v[90:91],v3 offset:13824
	v_mfma_f32_32x32x16_bf16 v[32:47], v[12:15], v[92:95], v[32:47]
	ds_read_b64_tr_b16 v[92:93],v3 offset:14336
	ds_read_b64_tr_b16 v[94:95],v3 offset:14848
	ds_read_b64_tr_b16 v[100:101],v3 offset:15360
	ds_read_b64_tr_b16 v[102:103],v3 offset:15872
	s_waitcnt lgkmcnt(0)
	v_mfma_f32_32x32x16_bf16 v[32:47], v[80:83], v[96:99], v[32:47]
	v_mfma_f32_32x32x16_bf16 v[16:31], v[4:7], v[84:87], v[16:31]
	v_mov_b32_e32 v3, v0
	s_nop 1
	v_permlane32_swap_b32_e32 v0, v3
	v_mfma_f32_32x32x16_bf16 v[16:31], v[8:11], v[88:91], v[16:31]
	v_mfma_f32_32x32x16_bf16 v[16:31], v[12:15], v[92:95], v[16:31]
	v_mfma_f32_32x32x16_bf16 v[16:31], v[80:83], v[100:103], v[16:31]
	s_and_saveexec_b64 s[4:5], s[2:3]
	v_add_f32_e32 v0, v0, v3
	ds_write_b32 v229, v0 offset:128
	s_or_b64 exec, exec, s[4:5]
	s_waitcnt lgkmcnt(0)
	ds_read_b128 v[4:7], v2 offset:128
	ds_read_b128 v[8:11], v2 offset:160
	s_lshl_b64 s[4:5], s[46:47], 12
	s_add_u32 s4, s64, s4
	s_addc_u32 s5, s65, s5
	s_lshl_b32 s6, s83, 8
	s_waitcnt lgkmcnt(1)
	v_rcp_f32_e32 v120, v4
	v_rcp_f32_e32 v119, v5
	v_rcp_f32_e32 v118, v6
	v_rcp_f32_e32 v117, v7
	s_waitcnt lgkmcnt(0)
	v_rcp_f32_e32 v116, v8
	ds_read_b128 v[4:7], v2 offset:192
	v_rcp_f32_e32 v115, v9
	v_rcp_f32_e32 v114, v10
	v_rcp_f32_e32 v112, v11
	ds_read_b128 v[8:11], v2 offset:224
	s_add_u32 s4, s4, s6
	s_addc_u32 s5, s5, 0
	s_lshl_b32 s6, s82, 12
	s_add_i32 s6, s6, 0
	s_add_i32 s6, s6, 0x12800
	v_lshlrev_b32_e32 v2, 1, v244
	v_add3_u32 v82, s6, v2, v250
	v_mul_f32_e32 v2, v64, v120
	s_waitcnt lgkmcnt(0)
	v_rcp_f32_e32 v107, v9
	v_cvt_pk_bf16_f32 v9, v2, s0
	v_mul_f32_e32 v2, v48, v120
	v_cvt_pk_bf16_f32 v83, v2, s0
	v_mul_f32_e32 v2, v65, v119
	v_cvt_pk_bf16_f32 v84, v2, s0
	v_mul_f32_e32 v2, v49, v119
	v_cvt_pk_bf16_f32 v85, v2, s0
	v_mul_f32_e32 v2, v66, v118
	v_cvt_pk_bf16_f32 v86, v2, s0
	v_mul_f32_e32 v2, v50, v118
	v_cvt_pk_bf16_f32 v87, v2, s0
	v_mul_f32_e32 v2, v67, v117
	v_cvt_pk_bf16_f32 v88, v2, s0
	v_mul_f32_e32 v2, v51, v117
	v_cvt_pk_bf16_f32 v89, v2, s0
	v_mul_f32_e32 v2, v68, v116
	v_cvt_pk_bf16_f32 v90, v2, s0
	v_mul_f32_e32 v2, v52, v116
	v_cvt_pk_bf16_f32 v91, v2, s0
	v_mul_f32_e32 v2, v69, v115
	v_cvt_pk_bf16_f32 v92, v2, s0
	v_mul_f32_e32 v2, v53, v115
	v_rcp_f32_e32 v113, v4
	v_cvt_pk_bf16_f32 v93, v2, s0
	v_mul_f32_e32 v2, v70, v114
	v_cvt_pk_bf16_f32 v94, v2, s0
	v_mul_f32_e32 v2, v54, v114
	v_rcp_f32_e32 v111, v5
	v_cvt_pk_bf16_f32 v95, v2, s0
	v_mul_f32_e32 v2, v71, v112
	v_cvt_pk_bf16_f32 v71, v2, s0
	v_mul_f32_e32 v2, v55, v112
	v_rcp_f32_e32 v110, v6
	v_cvt_pk_bf16_f32 v96, v2, s0
	v_mul_f32_e32 v2, v72, v113
	v_cvt_pk_bf16_f32 v72, v2, s0
	v_mul_f32_e32 v2, v56, v113
	v_rcp_f32_e32 v109, v7
	v_cvt_pk_bf16_f32 v97, v2, s0
	v_mul_f32_e32 v2, v73, v111
	v_cvt_pk_bf16_f32 v73, v2, s0
	v_mul_f32_e32 v2, v57, v111
	v_rcp_f32_e32 v108, v8
	v_cvt_pk_bf16_f32 v98, v2, s0
	v_mul_f32_e32 v2, v74, v110
	v_cvt_pk_bf16_f32 v74, v2, s0
	v_mul_f32_e32 v2, v58, v110
	v_cvt_pk_bf16_f32 v99, v2, s0
	v_mul_f32_e32 v2, v75, v109
	v_cvt_pk_bf16_f32 v75, v2, s0
	v_mul_f32_e32 v2, v59, v109
	v_rcp_f32_e32 v106, v10
	v_cvt_pk_bf16_f32 v100, v2, s0
	v_mul_f32_e32 v2, v76, v108
	v_cvt_pk_bf16_f32 v76, v2, s0
	v_mul_f32_e32 v2, v60, v108
	v_rcp_f32_e32 v105, v11
	v_cvt_pk_bf16_f32 v101, v2, s0
	v_mul_f32_e32 v2, v77, v107
	v_cvt_pk_bf16_f32 v77, v2, s0
	v_mul_f32_e32 v2, v61, v107
	v_mov_b32_e32 v0, v239
	v_cvt_pk_bf16_f32 v102, v2, s0
	v_mul_f32_e32 v2, v78, v106
	v_cvt_pk_bf16_f32 v78, v2, s0
	v_mul_f32_e32 v2, v62, v106
	v_ashrrev_i32_e32 v80, 3, v0
	v_lshlrev_b32_e32 v0, 3, v0
	v_cvt_pk_bf16_f32 v103, v2, s0
	v_mul_f32_e32 v2, v79, v105
	v_and_b32_e32 v8, 56, v0
	v_cvt_pk_bf16_f32 v79, v2, s0
	v_mul_f32_e32 v2, v63, v105
	v_lshlrev_b32_e32 v0, 1, v8
	v_cvt_pk_bf16_f32 v104, v2, s0
	v_add_u32_e32 v124, s6, v0
	ds_write_b16 v82, v9
	ds_write_b16 v82, v83 offset:64
	ds_write_b16 v82, v84 offset:128
	ds_write_b16 v82, v85 offset:192
	ds_write_b16 v82, v86 offset:256
	ds_write_b16 v82, v87 offset:320
	ds_write_b16 v82, v88 offset:384
	ds_write_b16 v82, v89 offset:448
	ds_write_b16 v82, v90 offset:1024
	ds_write_b16 v82, v91 offset:1088
	ds_write_b16 v82, v92 offset:1152
	ds_write_b16 v82, v93 offset:1216
	ds_write_b16 v82, v94 offset:1280
	ds_write_b16 v82, v95 offset:1344
	ds_write_b16 v82, v71 offset:1408
	ds_write_b16 v82, v96 offset:1472
	ds_write_b16 v82, v72 offset:2048
	ds_write_b16 v82, v97 offset:2112
	ds_write_b16 v82, v73 offset:2176
	ds_write_b16 v82, v98 offset:2240
	ds_write_b16 v82, v74 offset:2304
	ds_write_b16 v82, v99 offset:2368
	ds_write_b16 v82, v75 offset:2432
	ds_write_b16 v82, v100 offset:2496
	ds_write_b16 v82, v76 offset:3072
	ds_write_b16 v82, v101 offset:3136
	ds_write_b16 v82, v77 offset:3200
	ds_write_b16 v82, v102 offset:3264
	ds_write_b16 v82, v78 offset:3328
	ds_write_b16 v82, v103 offset:3392
	ds_write_b16 v82, v79 offset:3456
	ds_write_b16 v82, v104 offset:3520
	v_lshlrev_b32_e32 v2, 7, v80
	s_waitcnt lgkmcnt(0)
	v_add_u32_e32 v56, v124, v2
	ds_read_b128 v[2:5], v56
	s_cmp_gt_u32 s80, 3
	v_ashrrev_i32_e32 v81, 31, v80
	s_cselect_b64 s[48:49], -1, 0
	v_lshl_add_u64 v[6:7], s[4:5], 0, v[0:1]
	v_lshlrev_b64 v[10:11], 12, v[80:81]
	s_mov_b64 s[4:5], -1
	s_and_b64 vcc, exec, s[48:49]
	v_lshl_add_u64 v[10:11], v[6:7], 0, v[10:11]
	s_cbranch_vccz .LBB0_981
	global_load_dwordx4 v[12:15], v[10:11], off offset:-256
	global_load_dwordx4 v[136:139], v[10:11], off offset:-256
	global_load_dwordx4 v[140:143], v[10:11], off offset:-128
	v_add_co_u32_e32 v172, vcc, 0x8000, v10
	s_nop 1
	v_addc_co_u32_e32 v173, vcc, 0, v11, vcc
	global_load_dwordx4 v[144:147], v[172:173], off offset:-256
	global_load_dwordx4 v[148:151], v[172:173], off offset:-128
	v_add_co_u32_e32 v174, vcc, 0x10000, v10
	s_nop 1
	v_addc_co_u32_e32 v175, vcc, 0, v11, vcc
	global_load_dwordx4 v[152:155], v[174:175], off offset:-256
	global_load_dwordx4 v[156:159], v[174:175], off offset:-128
	v_add_co_u32_e32 v176, vcc, 0x18000, v10
	s_nop 1
	v_addc_co_u32_e32 v177, vcc, 0, v11, vcc
	global_load_dwordx4 v[160:163], v[176:177], off offset:-256
	global_load_dwordx4 v[164:167], v[176:177], off offset:-128
	s_waitcnt lgkmcnt(0)
	v_lshlrev_b32_e32 v48, 16, v2
	v_and_b32_e32 v49, 0xffff0000, v2
	v_and_b32_e32 v50, 0xffff0000, v3
	v_lshlrev_b32_e32 v51, 16, v3
	v_and_b32_e32 v52, 0xffff0000, v4
	v_lshlrev_b32_e32 v53, 16, v4
	v_and_b32_e32 v54, 0xffff0000, v5
	v_lshlrev_b32_e32 v55, 16, v5
	s_mov_b64 s[4:5], 0
	s_waitcnt vmcnt(0)
	v_lshlrev_b32_e32 v58, 16, v12
	v_and_b32_e32 v59, 0xffff0000, v12
	v_and_b32_e32 v12, 0xffff0000, v13
	v_lshlrev_b32_e32 v13, 16, v13
	v_pk_fma_f32 v[48:49], v[224:225], v[48:49], v[58:59] neg_lo:[1,0,0] neg_hi:[1,0,0]
	v_pk_fma_f32 v[12:13], v[224:225], v[50:51], v[12:13] neg_lo:[1,0,0] neg_hi:[1,0,0]
	v_pk_mul_f32 v[48:49], v[48:49], v[48:49]
	v_and_b32_e32 v60, 0xffff0000, v14
	v_lshlrev_b32_e32 v61, 16, v14
	v_pk_mul_f32 v[12:13], v[12:13], v[12:13]
	v_add_f32_e32 v48, v48, v49
	v_pk_fma_f32 v[50:51], v[224:225], v[52:53], v[60:61] neg_lo:[1,0,0] neg_hi:[1,0,0]
	v_add_f32_e32 v13, v13, v48
	v_and_b32_e32 v14, 0xffff0000, v15
	v_lshlrev_b32_e32 v15, 16, v15
	v_pk_mul_f32 v[50:51], v[50:51], v[50:51]
	v_add_f32_e32 v12, v12, v13
	v_pk_fma_f32 v[14:15], v[224:225], v[54:55], v[14:15] neg_lo:[1,0,0] neg_hi:[1,0,0]
	v_add_f32_e32 v12, v51, v12
	v_pk_mul_f32 v[14:15], v[14:15], v[14:15]
	v_add_f32_e32 v12, v50, v12
	v_add_f32_e32 v12, v15, v12
	v_add_f32_e32 v121, v14, v12

.LBB0_983:
	v_add_u32_e32 v52, 8, v80
	s_waitcnt lgkmcnt(0)
	v_lshlrev_b32_e32 v2, 7, v52
	v_add_u32_e32 v58, v124, v2
	ds_read_b128 v[2:5], v58
	v_ashrrev_i32_e32 v53, 31, v52
	v_lshlrev_b64 v[12:13], 12, v[52:53]
	v_cndmask_b32_e64 v14, 0, 1, s[48:49]
	s_mov_b64 s[50:51], -1
	v_cmp_ne_u32_e64 s[4:5], 1, v14
	s_andn2_b64 vcc, exec, s[48:49]
	v_lshl_add_u64 v[12:13], v[6:7], 0, v[12:13]
	s_cbranch_vccnz .LBB0_985
	v_mov_b32_e32 v48, v144
	v_mov_b32_e32 v49, v145
	v_mov_b32_e32 v50, v146
	v_mov_b32_e32 v51, v147
	s_waitcnt lgkmcnt(0)
	v_lshlrev_b32_e32 v14, 16, v2
	v_and_b32_e32 v15, 0xffff0000, v2
	v_and_b32_e32 v54, 0xffff0000, v3
	v_lshlrev_b32_e32 v55, 16, v3
	v_and_b32_e32 v60, 0xffff0000, v4
	v_lshlrev_b32_e32 v61, 16, v4
	v_and_b32_e32 v62, 0xffff0000, v5
	v_lshlrev_b32_e32 v63, 16, v5
	s_mov_b64 s[50:51], 0
	s_waitcnt vmcnt(0)
	v_lshlrev_b32_e32 v64, 16, v48
	v_and_b32_e32 v65, 0xffff0000, v48
	v_and_b32_e32 v48, 0xffff0000, v49
	v_lshlrev_b32_e32 v49, 16, v49
	v_pk_fma_f32 v[14:15], v[224:225], v[14:15], v[64:65] neg_lo:[1,0,0] neg_hi:[1,0,0]
	v_pk_fma_f32 v[48:49], v[224:225], v[54:55], v[48:49] neg_lo:[1,0,0] neg_hi:[1,0,0]
	v_pk_mul_f32 v[14:15], v[14:15], v[14:15]
	v_and_b32_e32 v66, 0xffff0000, v50
	v_lshlrev_b32_e32 v67, 16, v50
	v_pk_mul_f32 v[48:49], v[48:49], v[48:49]
	v_add_f32_e32 v14, v14, v15
	v_pk_fma_f32 v[54:55], v[224:225], v[60:61], v[66:67] neg_lo:[1,0,0] neg_hi:[1,0,0]
	v_add_f32_e32 v14, v49, v14
	v_and_b32_e32 v50, 0xffff0000, v51
	v_lshlrev_b32_e32 v51, 16, v51
	v_pk_mul_f32 v[54:55], v[54:55], v[54:55]
	v_add_f32_e32 v14, v48, v14
	v_pk_fma_f32 v[50:51], v[224:225], v[62:63], v[50:51] neg_lo:[1,0,0] neg_hi:[1,0,0]
	v_add_f32_e32 v14, v55, v14
	v_pk_mul_f32 v[50:51], v[50:51], v[50:51]
	v_add_f32_e32 v14, v54, v14
	v_add_f32_e32 v14, v51, v14
	v_add_f32_e32 v122, v50, v14

.LBB0_987:
	v_add_u32_e32 v50, 16, v80
	s_waitcnt lgkmcnt(0)
	v_lshlrev_b32_e32 v2, 7, v50
	v_add_u32_e32 v57, v124, v2
	ds_read_b128 v[2:5], v57
	v_ashrrev_i32_e32 v51, 31, v50
	v_lshlrev_b64 v[14:15], 12, v[50:51]
	s_mov_b64 s[50:51], -1
	s_and_b64 vcc, exec, s[4:5]
	v_lshl_add_u64 v[14:15], v[6:7], 0, v[14:15]
	s_cbranch_vccnz .LBB0_989
	v_mov_b32_e32 v60, v152
	v_mov_b32_e32 v61, v153
	v_mov_b32_e32 v62, v154
	v_mov_b32_e32 v63, v155
	s_waitcnt lgkmcnt(0)
	v_lshlrev_b32_e32 v48, 16, v2
	v_and_b32_e32 v49, 0xffff0000, v2
	v_and_b32_e32 v54, 0xffff0000, v3
	v_lshlrev_b32_e32 v55, 16, v3
	v_and_b32_e32 v64, 0xffff0000, v4
	v_lshlrev_b32_e32 v65, 16, v4
	v_and_b32_e32 v66, 0xffff0000, v5
	v_lshlrev_b32_e32 v67, 16, v5
	s_mov_b64 s[50:51], 0
	s_waitcnt vmcnt(0)
	v_lshlrev_b32_e32 v68, 16, v60
	v_and_b32_e32 v69, 0xffff0000, v60
	v_and_b32_e32 v60, 0xffff0000, v61
	v_lshlrev_b32_e32 v61, 16, v61
	v_pk_fma_f32 v[48:49], v[224:225], v[48:49], v[68:69] neg_lo:[1,0,0] neg_hi:[1,0,0]
	v_pk_fma_f32 v[54:55], v[224:225], v[54:55], v[60:61] neg_lo:[1,0,0] neg_hi:[1,0,0]
	v_pk_mul_f32 v[48:49], v[48:49], v[48:49]
	v_and_b32_e32 v126, 0xffff0000, v62
	v_lshlrev_b32_e32 v127, 16, v62
	v_pk_mul_f32 v[54:55], v[54:55], v[54:55]
	v_add_f32_e32 v48, v48, v49
	v_pk_fma_f32 v[60:61], v[224:225], v[64:65], v[126:127] neg_lo:[1,0,0] neg_hi:[1,0,0]
	v_add_f32_e32 v48, v55, v48
	v_and_b32_e32 v62, 0xffff0000, v63
	v_lshlrev_b32_e32 v63, 16, v63
	v_pk_mul_f32 v[60:61], v[60:61], v[60:61]
	v_add_f32_e32 v48, v54, v48
	v_pk_fma_f32 v[62:63], v[224:225], v[66:67], v[62:63] neg_lo:[1,0,0] neg_hi:[1,0,0]
	v_add_f32_e32 v48, v61, v48
	v_pk_mul_f32 v[62:63], v[62:63], v[62:63]
	v_add_f32_e32 v48, v60, v48
	v_add_f32_e32 v48, v63, v48
	v_add_f32_e32 v123, v62, v48

.LBB0_991:
	v_add_u32_e32 v54, 24, v80
	s_waitcnt lgkmcnt(0)
	v_lshlrev_b32_e32 v2, 7, v54
	v_add_u32_e32 v59, v124, v2
	ds_read_b128 v[2:5], v59
	v_ashrrev_i32_e32 v55, 31, v54
	v_lshlrev_b64 v[48:49], 12, v[54:55]
	s_mov_b64 s[50:51], -1
	s_and_b64 vcc, exec, s[4:5]
	v_lshl_add_u64 v[48:49], v[6:7], 0, v[48:49]
	s_cbranch_vccnz .LBB0_993
	v_mov_b32_e32 v60, v160
	v_mov_b32_e32 v61, v161
	v_mov_b32_e32 v62, v162
	v_mov_b32_e32 v63, v163
	s_waitcnt lgkmcnt(0)
	v_lshlrev_b32_e32 v6, 16, v2
	v_and_b32_e32 v7, 0xffff0000, v2
	v_and_b32_e32 v64, 0xffff0000, v3
	v_lshlrev_b32_e32 v65, 16, v3
	v_and_b32_e32 v66, 0xffff0000, v4
	v_lshlrev_b32_e32 v67, 16, v4
	v_and_b32_e32 v68, 0xffff0000, v5
	v_lshlrev_b32_e32 v69, 16, v5
	s_mov_b64 s[50:51], 0
	s_waitcnt vmcnt(0)
	v_lshlrev_b32_e32 v124, 16, v60
	v_and_b32_e32 v125, 0xffff0000, v60
	v_and_b32_e32 v60, 0xffff0000, v61
	v_lshlrev_b32_e32 v61, 16, v61
	v_pk_fma_f32 v[6:7], v[224:225], v[6:7], v[124:125] neg_lo:[1,0,0] neg_hi:[1,0,0]
	v_pk_fma_f32 v[60:61], v[224:225], v[64:65], v[60:61] neg_lo:[1,0,0] neg_hi:[1,0,0]
	v_pk_mul_f32 v[6:7], v[6:7], v[6:7]
	v_and_b32_e32 v126, 0xffff0000, v62
	v_lshlrev_b32_e32 v127, 16, v62
	v_pk_mul_f32 v[60:61], v[60:61], v[60:61]
	v_add_f32_e32 v6, v6, v7
	v_pk_fma_f32 v[64:65], v[224:225], v[66:67], v[126:127] neg_lo:[1,0,0] neg_hi:[1,0,0]
	v_add_f32_e32 v6, v61, v6
	v_and_b32_e32 v62, 0xffff0000, v63
	v_lshlrev_b32_e32 v63, 16, v63
	v_pk_mul_f32 v[64:65], v[64:65], v[64:65]
	v_add_f32_e32 v6, v60, v6
	v_pk_fma_f32 v[62:63], v[224:225], v[68:69], v[62:63] neg_lo:[1,0,0] neg_hi:[1,0,0]
	v_add_f32_e32 v6, v65, v6
	v_pk_mul_f32 v[62:63], v[62:63], v[62:63]
	v_add_f32_e32 v6, v64, v6
	v_add_f32_e32 v6, v63, v6
	v_add_f32_e32 v6, v62, v6

.LBB0_995:
	s_waitcnt lgkmcnt(0)
	s_nop 0
	v_mul_f32_e32 v2, v32, v120
	v_cvt_pk_bf16_f32 v32, v2, s0
	v_mul_f32_e32 v2, v16, v120
	v_cvt_pk_bf16_f32 v60, v2, s0
	v_mul_f32_e32 v2, v33, v119
	v_cvt_pk_bf16_f32 v33, v2, s0
	v_mul_f32_e32 v2, v17, v119
	v_cvt_pk_bf16_f32 v61, v2, s0
	v_mul_f32_e32 v2, v34, v118
	v_cvt_pk_bf16_f32 v34, v2, s0
	v_mul_f32_e32 v2, v18, v118
	v_cvt_pk_bf16_f32 v62, v2, s0
	v_mul_f32_e32 v2, v35, v117
	v_cvt_pk_bf16_f32 v35, v2, s0
	v_mul_f32_e32 v2, v19, v117
	v_cvt_pk_bf16_f32 v19, v2, s0
	v_mul_f32_e32 v2, v36, v116
	v_cvt_pk_bf16_f32 v36, v2, s0
	v_mul_f32_e32 v2, v20, v116
	v_cvt_pk_bf16_f32 v63, v2, s0
	v_mul_f32_e32 v2, v37, v115
	v_cvt_pk_bf16_f32 v37, v2, s0
	v_mul_f32_e32 v2, v21, v115
	v_cvt_pk_bf16_f32 v64, v2, s0
	v_mul_f32_e32 v2, v38, v114
	v_cvt_pk_bf16_f32 v38, v2, s0
	v_mul_f32_e32 v2, v22, v114
	v_cvt_pk_bf16_f32 v65, v2, s0
	v_mul_f32_e32 v2, v39, v112
	v_cvt_pk_bf16_f32 v39, v2, s0
	v_mul_f32_e32 v2, v23, v112
	v_cvt_pk_bf16_f32 v23, v2, s0
	v_mul_f32_e32 v2, v40, v113
	v_cvt_pk_bf16_f32 v40, v2, s0
	v_mul_f32_e32 v2, v24, v113
	v_cvt_pk_bf16_f32 v66, v2, s0
	v_mul_f32_e32 v2, v41, v111
	v_cvt_pk_bf16_f32 v41, v2, s0
	v_mul_f32_e32 v2, v25, v111
	v_cvt_pk_bf16_f32 v67, v2, s0
	v_mul_f32_e32 v2, v42, v110
	v_cvt_pk_bf16_f32 v42, v2, s0
	v_mul_f32_e32 v2, v26, v110
	v_cvt_pk_bf16_f32 v68, v2, s0
	v_mul_f32_e32 v2, v43, v109
	v_cvt_pk_bf16_f32 v43, v2, s0
	v_mul_f32_e32 v2, v27, v109
	v_cvt_pk_bf16_f32 v69, v2, s0
	v_mul_f32_e32 v2, v44, v108
	v_cvt_pk_bf16_f32 v44, v2, s0
	v_mul_f32_e32 v2, v28, v108
	v_cvt_pk_bf16_f32 v70, v2, s0
	v_mul_f32_e32 v2, v45, v107
	v_cvt_pk_bf16_f32 v45, v2, s0
	v_mul_f32_e32 v2, v29, v107
	v_cvt_pk_bf16_f32 v29, v2, s0
	v_mul_f32_e32 v2, v46, v106
	v_cvt_pk_bf16_f32 v46, v2, s0
	v_mul_f32_e32 v2, v30, v106
	v_cvt_pk_bf16_f32 v30, v2, s0
	v_mul_f32_e32 v2, v47, v105
	v_cvt_pk_bf16_f32 v47, v2, s0
	v_mul_f32_e32 v2, v31, v105
	v_cvt_pk_bf16_f32 v31, v2, s0
	s_waitcnt lgkmcnt(0)
	ds_write_b16 v82, v32
	ds_write_b16 v82, v60 offset:64
	ds_write_b16 v82, v33 offset:128
	ds_write_b16 v82, v61 offset:192
	ds_write_b16 v82, v34 offset:256
	ds_write_b16 v82, v62 offset:320
	ds_write_b16 v82, v35 offset:384
	ds_write_b16 v82, v19 offset:448
	ds_write_b16 v82, v36 offset:1024
	ds_write_b16 v82, v63 offset:1088
	ds_write_b16 v82, v37 offset:1152
	ds_write_b16 v82, v64 offset:1216
	ds_write_b16 v82, v38 offset:1280
	ds_write_b16 v82, v65 offset:1344
	ds_write_b16 v82, v39 offset:1408
	ds_write_b16 v82, v23 offset:1472
	ds_write_b16 v82, v40 offset:2048
	ds_write_b16 v82, v66 offset:2112
	ds_write_b16 v82, v41 offset:2176
	ds_write_b16 v82, v67 offset:2240
	ds_write_b16 v82, v42 offset:2304
	ds_write_b16 v82, v68 offset:2368
	ds_write_b16 v82, v43 offset:2432
	ds_write_b16 v82, v69 offset:2496
	ds_write_b16 v82, v44 offset:3072
	ds_write_b16 v82, v70 offset:3136
	ds_write_b16 v82, v45 offset:3200
	ds_write_b16 v82, v29 offset:3264
	ds_write_b16 v82, v46 offset:3328
	ds_write_b16 v82, v30 offset:3392
	ds_write_b16 v82, v47 offset:3456
	ds_write_b16 v82, v31 offset:3520
	s_waitcnt lgkmcnt(0)
	ds_read_b128 v[2:5], v56
	s_and_b64 vcc, exec, s[4:5]
	s_mov_b64 s[50:51], -1
	s_cbranch_vccnz .LBB0_997
	v_mov_b32_e32 v24, v140
	v_mov_b32_e32 v25, v141
	v_mov_b32_e32 v26, v142
	v_mov_b32_e32 v27, v143
	s_waitcnt lgkmcnt(0)
	v_and_b32_e32 v16, 0xffff0000, v2
	v_lshlrev_b32_e32 v17, 16, v2
	v_and_b32_e32 v20, 0xffff0000, v3
	v_lshlrev_b32_e32 v21, 16, v3
	v_and_b32_e32 v106, 0xffff0000, v4
	v_lshlrev_b32_e32 v107, 16, v4
	v_and_b32_e32 v108, 0xffff0000, v5
	v_lshlrev_b32_e32 v109, 16, v5
	s_waitcnt vmcnt(0)
	v_and_b32_e32 v110, 0xffff0000, v24
	v_lshlrev_b32_e32 v111, 16, v24
	v_pk_fma_f32 v[16:17], v[224:225], v[16:17], v[110:111] neg_lo:[1,0,0] neg_hi:[1,0,0]
	v_and_b32_e32 v24, 0xffff0000, v25
	v_lshlrev_b32_e32 v25, 16, v25
	v_pk_mul_f32 v[16:17], v[16:17], v[16:17]
	v_pk_fma_f32 v[20:21], v[224:225], v[20:21], v[24:25] neg_lo:[1,0,0] neg_hi:[1,0,0]
	v_add_f32_e32 v7, v121, v17
	v_and_b32_e32 v112, 0xffff0000, v26
	v_lshlrev_b32_e32 v113, 16, v26
	v_pk_mul_f32 v[20:21], v[20:21], v[20:21]
	v_add_f32_e32 v7, v16, v7
	v_pk_fma_f32 v[24:25], v[224:225], v[106:107], v[112:113] neg_lo:[1,0,0] neg_hi:[1,0,0]
	v_add_f32_e32 v7, v21, v7
	v_and_b32_e32 v26, 0xffff0000, v27
	v_lshlrev_b32_e32 v27, 16, v27
	v_pk_mul_f32 v[24:25], v[24:25], v[24:25]
	v_add_f32_e32 v7, v20, v7
	v_pk_fma_f32 v[26:27], v[224:225], v[108:109], v[26:27] neg_lo:[1,0,0] neg_hi:[1,0,0]
	v_add_f32_e32 v7, v25, v7
	v_pk_mul_f32 v[26:27], v[26:27], v[26:27]
	v_add_f32_e32 v7, v24, v7
	v_add_f32_e32 v7, v27, v7
	v_add_f32_e32 v16, v26, v7
	s_cbranch_execnz .LBB0_999
	s_branch .LBB0_998

.LBB0_999:
	s_waitcnt lgkmcnt(0)
	ds_read_b128 v[2:5], v58
	s_and_b64 vcc, exec, s[4:5]
	s_mov_b64 s[50:51], -1
	s_cbranch_vccnz .LBB0_1001
	v_mov_b32_e32 v24, v148
	v_mov_b32_e32 v25, v149
	v_mov_b32_e32 v26, v150
	v_mov_b32_e32 v27, v151
	s_waitcnt lgkmcnt(0)
	v_and_b32_e32 v20, 0xffff0000, v2
	v_lshlrev_b32_e32 v21, 16, v2
	v_and_b32_e32 v106, 0xffff0000, v3
	v_lshlrev_b32_e32 v107, 16, v3
	v_and_b32_e32 v108, 0xffff0000, v4
	v_lshlrev_b32_e32 v109, 16, v4
	v_and_b32_e32 v110, 0xffff0000, v5
	v_lshlrev_b32_e32 v111, 16, v5
	s_waitcnt vmcnt(0)
	v_and_b32_e32 v112, 0xffff0000, v24
	v_lshlrev_b32_e32 v113, 16, v24
	v_pk_fma_f32 v[20:21], v[224:225], v[20:21], v[112:113] neg_lo:[1,0,0] neg_hi:[1,0,0]
	v_and_b32_e32 v24, 0xffff0000, v25
	v_lshlrev_b32_e32 v25, 16, v25
	v_pk_mul_f32 v[20:21], v[20:21], v[20:21]
	v_pk_fma_f32 v[24:25], v[224:225], v[106:107], v[24:25] neg_lo:[1,0,0] neg_hi:[1,0,0]
	v_add_f32_e32 v7, v122, v21
	v_and_b32_e32 v114, 0xffff0000, v26
	v_lshlrev_b32_e32 v115, 16, v26
	v_pk_mul_f32 v[24:25], v[24:25], v[24:25]
	v_add_f32_e32 v7, v20, v7
	v_pk_fma_f32 v[106:107], v[224:225], v[108:109], v[114:115] neg_lo:[1,0,0] neg_hi:[1,0,0]
	v_add_f32_e32 v7, v25, v7
	v_and_b32_e32 v26, 0xffff0000, v27
	v_lshlrev_b32_e32 v27, 16, v27
	v_pk_mul_f32 v[106:107], v[106:107], v[106:107]
	v_add_f32_e32 v7, v24, v7
	v_pk_fma_f32 v[26:27], v[224:225], v[110:111], v[26:27] neg_lo:[1,0,0] neg_hi:[1,0,0]
	v_add_f32_e32 v7, v107, v7
	v_pk_mul_f32 v[26:27], v[26:27], v[26:27]
	v_add_f32_e32 v7, v106, v7
	v_add_f32_e32 v7, v27, v7
	v_add_f32_e32 v18, v26, v7
	s_cbranch_execnz .LBB0_1003
	s_branch .LBB0_1002

.LBB0_1003:
	s_waitcnt lgkmcnt(0)
	ds_read_b128 v[2:5], v57
	s_and_b64 vcc, exec, s[4:5]
	s_mov_b64 s[50:51], -1
	s_cbranch_vccnz .LBB0_1005
	v_mov_b32_e32 v24, v156
	v_mov_b32_e32 v25, v157
	v_mov_b32_e32 v26, v158
	v_mov_b32_e32 v27, v159
	s_waitcnt lgkmcnt(0)
	v_and_b32_e32 v20, 0xffff0000, v2
	v_lshlrev_b32_e32 v21, 16, v2
	v_and_b32_e32 v106, 0xffff0000, v3
	v_lshlrev_b32_e32 v107, 16, v3
	v_and_b32_e32 v108, 0xffff0000, v4
	v_lshlrev_b32_e32 v109, 16, v4
	v_and_b32_e32 v110, 0xffff0000, v5
	v_lshlrev_b32_e32 v111, 16, v5
	s_waitcnt vmcnt(0)
	v_and_b32_e32 v112, 0xffff0000, v24
	v_lshlrev_b32_e32 v113, 16, v24
	v_pk_fma_f32 v[20:21], v[224:225], v[20:21], v[112:113] neg_lo:[1,0,0] neg_hi:[1,0,0]
	v_and_b32_e32 v24, 0xffff0000, v25
	v_lshlrev_b32_e32 v25, 16, v25
	v_pk_mul_f32 v[20:21], v[20:21], v[20:21]
	v_pk_fma_f32 v[24:25], v[224:225], v[106:107], v[24:25] neg_lo:[1,0,0] neg_hi:[1,0,0]
	v_add_f32_e32 v7, v123, v21
	v_and_b32_e32 v114, 0xffff0000, v26
	v_lshlrev_b32_e32 v115, 16, v26
	v_pk_mul_f32 v[24:25], v[24:25], v[24:25]
	v_add_f32_e32 v7, v20, v7
	v_pk_fma_f32 v[106:107], v[224:225], v[108:109], v[114:115] neg_lo:[1,0,0] neg_hi:[1,0,0]
	v_add_f32_e32 v7, v25, v7
	v_and_b32_e32 v26, 0xffff0000, v27
	v_lshlrev_b32_e32 v27, 16, v27
	v_pk_mul_f32 v[106:107], v[106:107], v[106:107]
	v_add_f32_e32 v7, v24, v7
	v_pk_fma_f32 v[26:27], v[224:225], v[110:111], v[26:27] neg_lo:[1,0,0] neg_hi:[1,0,0]
	v_add_f32_e32 v7, v107, v7
	v_pk_mul_f32 v[26:27], v[26:27], v[26:27]
	v_add_f32_e32 v7, v106, v7
	v_add_f32_e32 v7, v27, v7
	v_add_f32_e32 v22, v26, v7
	s_cbranch_execnz .LBB0_1007
	s_branch .LBB0_1006

.LBB0_1007:
	s_waitcnt lgkmcnt(0)
	ds_read_b128 v[2:5], v59
	s_and_b64 vcc, exec, s[4:5]
	s_mov_b64 s[4:5], -1
	s_cbranch_vccnz .LBB0_1009
	v_mov_b32_e32 v24, v164
	v_mov_b32_e32 v25, v165
	v_mov_b32_e32 v26, v166
	v_mov_b32_e32 v27, v167
	s_waitcnt lgkmcnt(0)
	v_and_b32_e32 v20, 0xffff0000, v2
	v_lshlrev_b32_e32 v21, 16, v2
	v_and_b32_e32 v106, 0xffff0000, v3
	v_lshlrev_b32_e32 v107, 16, v3
	v_and_b32_e32 v108, 0xffff0000, v4
	v_lshlrev_b32_e32 v109, 16, v4
	v_and_b32_e32 v110, 0xffff0000, v5
	v_lshlrev_b32_e32 v111, 16, v5
	s_waitcnt vmcnt(0)
	v_and_b32_e32 v112, 0xffff0000, v24
	v_lshlrev_b32_e32 v113, 16, v24
	v_pk_fma_f32 v[20:21], v[224:225], v[20:21], v[112:113] neg_lo:[1,0,0] neg_hi:[1,0,0]
	v_and_b32_e32 v24, 0xffff0000, v25
	v_lshlrev_b32_e32 v25, 16, v25
	v_pk_mul_f32 v[20:21], v[20:21], v[20:21]
	v_pk_fma_f32 v[24:25], v[224:225], v[106:107], v[24:25] neg_lo:[1,0,0] neg_hi:[1,0,0]
	v_add_f32_e32 v7, v6, v21
	v_and_b32_e32 v114, 0xffff0000, v26
	v_lshlrev_b32_e32 v115, 16, v26
	v_pk_mul_f32 v[24:25], v[24:25], v[24:25]
	v_add_f32_e32 v7, v20, v7
	v_pk_fma_f32 v[106:107], v[224:225], v[108:109], v[114:115] neg_lo:[1,0,0] neg_hi:[1,0,0]
	v_add_f32_e32 v7, v25, v7
	v_and_b32_e32 v26, 0xffff0000, v27
	v_lshlrev_b32_e32 v27, 16, v27
	v_pk_mul_f32 v[106:107], v[106:107], v[106:107]
	v_add_f32_e32 v7, v24, v7
	v_pk_fma_f32 v[26:27], v[224:225], v[110:111], v[26:27] neg_lo:[1,0,0] neg_hi:[1,0,0]
	v_add_f32_e32 v7, v107, v7
	v_pk_mul_f32 v[26:27], v[26:27], v[26:27]
	v_add_f32_e32 v7, v106, v7
	v_add_f32_e32 v7, v27, v7
	v_add_f32_e32 v28, v26, v7
	s_cbranch_execz .LBB0_1010
	s_branch .LBB0_1011

.LBB0_1011:
	s_waitcnt lgkmcnt(0)
	s_and_b64 vcc, exec, s[48:49]
	s_cbranch_vccz .LBB0_894
	ds_write_b16 v82, v9
	ds_write_b16 v82, v83 offset:64
	ds_write_b16 v82, v84 offset:128
	ds_write_b16 v82, v85 offset:192
	ds_write_b16 v82, v86 offset:256
	ds_write_b16 v82, v87 offset:320
	ds_write_b16 v82, v88 offset:384
	ds_write_b16 v82, v89 offset:448
	ds_write_b16 v82, v90 offset:1024
	ds_write_b16 v82, v91 offset:1088
	ds_write_b16 v82, v92 offset:1152
	ds_write_b16 v82, v93 offset:1216
	ds_write_b16 v82, v94 offset:1280
	ds_write_b16 v82, v95 offset:1344
	ds_write_b16 v82, v71 offset:1408
	ds_write_b16 v82, v96 offset:1472
	ds_write_b16 v82, v72 offset:2048
	ds_write_b16 v82, v97 offset:2112
	ds_write_b16 v82, v73 offset:2176
	ds_write_b16 v82, v98 offset:2240
	ds_write_b16 v82, v74 offset:2304
	ds_write_b16 v82, v99 offset:2368
	ds_write_b16 v82, v75 offset:2432
	ds_write_b16 v82, v100 offset:2496
	ds_write_b16 v82, v76 offset:3072
	ds_write_b16 v82, v101 offset:3136
	ds_write_b16 v82, v77 offset:3200
	ds_write_b16 v82, v102 offset:3264
	ds_write_b16 v82, v78 offset:3328
	ds_write_b16 v82, v103 offset:3392
	ds_write_b16 v82, v79 offset:3456
	ds_write_b16 v82, v104 offset:3520
	s_waitcnt lgkmcnt(0)
	v_mov_b32_e32 v72, v136
	v_mov_b32_e32 v73, v137
	v_mov_b32_e32 v74, v138
	v_mov_b32_e32 v75, v139
	v_lshlrev_b32_e32 v71, 2, v8
	global_load_dwordx4 v[6:9], v71, s[8:9]
	s_waitcnt lgkmcnt(14)
	global_load_dwordx4 v[2:5], v71, s[8:9] offset:16
	ds_bpermute_b32 v17, v241, v16
	v_mov_b32_e32 v90, 0x358637bd
	s_lshl_b32 s4, s88, 1
	s_add_u32 s4, s66, s4
	s_addc_u32 s5, s67, 0
	s_waitcnt lgkmcnt(0)
	v_add_f32_e32 v16, v16, v17
	ds_bpermute_b32 v17, v242, v16
	v_lshl_add_u64 v[24:25], s[4:5], 0, v[0:1]
	ds_read_b128 v[76:79], v56
	ds_read_b128 v[84:87], v58
	v_lshl_add_u64 v[54:55], s[46:47], 0, v[54:55]
	v_lshlrev_b64 v[54:55], 11, v[54:55]
	s_waitcnt lgkmcnt(2)
	v_add_f32_e32 v16, v16, v17
	ds_bpermute_b32 v17, v243, v16
	s_waitcnt lgkmcnt(0)
	v_add_f32_e32 v16, v16, v17
	v_fmamk_f32 v16, v16, 0x3c000000, v90
	v_mul_f32_e32 v17, 0x4f800000, v16
	v_cmp_gt_f32_e32 vcc, s74, v16
	s_nop 1
	v_cndmask_b32_e32 v16, v16, v17, vcc
	v_sqrt_f32_e32 v17, v16
	s_nop 0
	v_add_u32_e32 v0, -1, v17
	v_add_u32_e32 v20, 1, v17
	v_fma_f32 v21, -v0, v17, v16
	v_fma_f32 v26, -v20, v17, v16
	v_cmp_ge_f32_e64 s[4:5], 0, v21
	s_nop 1
	v_cndmask_b32_e64 v0, v17, v0, s[4:5]
	v_cmp_lt_f32_e64 s[4:5], 0, v26
	s_nop 1
	v_cndmask_b32_e64 v0, v0, v20, s[4:5]
	v_mul_f32_e32 v17, 0x37800000, v0
	v_cndmask_b32_e32 v0, v0, v17, vcc
	v_cmp_class_f32_e32 vcc, v16, v254
	s_nop 1
	v_cndmask_b32_e32 v0, v0, v16, vcc
	v_div_scale_f32 v17, s[4:5], v0, v0, s75
	v_rcp_f32_e32 v20, v17
	v_div_scale_f32 v21, vcc, s75, v0, s75
	v_lshlrev_b32_e32 v16, 16, v76
	v_fma_f32 v26, -v17, v20, 1.0
	v_fmac_f32_e32 v20, v26, v20
	v_mul_f32_e32 v26, v21, v20
	v_fma_f32 v27, -v17, v26, v21
	v_fmac_f32_e32 v26, v27, v20
	v_fma_f32 v17, -v17, v26, v21
	v_div_fmas_f32 v17, v17, v20, v26
	v_div_fixup_f32 v0, v17, v0, s75
	v_and_b32_e32 v17, 0xffff0000, v76
	v_lshlrev_b32_e32 v26, 16, v85
	v_and_b32_e32 v27, 0xffff0000, v85
	s_waitcnt vmcnt(2)
	v_lshlrev_b32_e32 v20, 16, v72
	v_and_b32_e32 v21, 0xffff0000, v72
	v_pk_fma_f32 v[16:17], v[224:225], v[16:17], v[20:21] neg_lo:[1,0,0] neg_hi:[1,0,0]
	v_lshlrev_b32_e32 v20, 16, v77
	v_pk_mul_f32 v[16:17], v[0:1], v[16:17] op_sel_hi:[0,1]
	s_waitcnt vmcnt(1)
	v_pk_mul_f32 v[16:17], v[6:7], v[16:17]
	v_and_b32_e32 v21, 0xffff0000, v77
	v_cvt_pk_bf16_f32 v72, v16, v17
	v_lshlrev_b32_e32 v16, 16, v73
	v_and_b32_e32 v17, 0xffff0000, v73
	v_pk_fma_f32 v[16:17], v[224:225], v[20:21], v[16:17] neg_lo:[1,0,0] neg_hi:[1,0,0]
	v_lshlrev_b32_e32 v20, 16, v78
	v_pk_mul_f32 v[16:17], v[0:1], v[16:17] op_sel_hi:[0,1]
	v_pk_mul_f32 v[16:17], v[8:9], v[16:17]
	v_and_b32_e32 v21, 0xffff0000, v78
	v_cvt_pk_bf16_f32 v73, v16, v17
	v_lshlrev_b32_e32 v16, 16, v74
	v_and_b32_e32 v17, 0xffff0000, v74
	v_pk_fma_f32 v[16:17], v[224:225], v[20:21], v[16:17] neg_lo:[1,0,0] neg_hi:[1,0,0]
	v_lshlrev_b32_e32 v20, 16, v79
	v_pk_mul_f32 v[16:17], v[0:1], v[16:17] op_sel_hi:[0,1]
	s_waitcnt vmcnt(0)
	v_pk_mul_f32 v[16:17], v[2:3], v[16:17]
	v_and_b32_e32 v21, 0xffff0000, v79
	v_cvt_pk_bf16_f32 v74, v16, v17
	v_lshlrev_b32_e32 v16, 16, v75
	v_and_b32_e32 v17, 0xffff0000, v75
	v_pk_fma_f32 v[16:17], v[224:225], v[20:21], v[16:17] neg_lo:[1,0,0] neg_hi:[1,0,0]
	ds_bpermute_b32 v20, v241, v18
	v_pk_mul_f32 v[16:17], v[0:1], v[16:17] op_sel_hi:[0,1]
	v_pk_mul_f32 v[16:17], v[16:17], v[4:5]
	s_waitcnt lgkmcnt(0)
	v_add_f32_e32 v18, v18, v20
	v_cvt_pk_bf16_f32 v75, v16, v17
	v_lshl_add_u64 v[16:17], s[46:47], 0, v[80:81]
	v_lshlrev_b64 v[16:17], 11, v[16:17]
	v_lshl_add_u64 v[16:17], v[24:25], 0, v[16:17]
	global_store_dwordx4 v[16:17], v[72:75], off
	s_nop 1
	v_mov_b32_e32 v72, v144
	v_mov_b32_e32 v73, v145
	v_mov_b32_e32 v74, v146
	v_mov_b32_e32 v75, v147
	ds_bpermute_b32 v20, v242, v18
	s_waitcnt lgkmcnt(0)
	v_add_f32_e32 v18, v18, v20
	ds_bpermute_b32 v21, v243, v18
	v_lshlrev_b32_e32 v20, 16, v84
	s_waitcnt lgkmcnt(0)
	v_add_f32_e32 v18, v18, v21
	v_fmamk_f32 v18, v18, 0x3c000000, v90
	v_mul_f32_e32 v21, 0x4f800000, v18
	v_cmp_gt_f32_e32 vcc, s74, v18
	s_nop 1
	v_cndmask_b32_e32 v18, v18, v21, vcc
	v_sqrt_f32_e32 v76, v18
	v_and_b32_e32 v21, 0xffff0000, v84
	v_add_u32_e32 v77, -1, v76
	v_add_u32_e32 v78, 1, v76
	v_fma_f32 v79, -v77, v76, v18
	v_fma_f32 v80, -v78, v76, v18
	v_cmp_ge_f32_e64 s[4:5], 0, v79
	s_nop 1
	v_cndmask_b32_e64 v76, v76, v77, s[4:5]
	v_cmp_lt_f32_e64 s[4:5], 0, v80
	s_nop 1
	v_cndmask_b32_e64 v76, v76, v78, s[4:5]
	v_mul_f32_e32 v77, 0x37800000, v76
	v_cndmask_b32_e32 v76, v76, v77, vcc
	v_cmp_class_f32_e32 vcc, v18, v254
	s_nop 1
	v_cndmask_b32_e32 v18, v76, v18, vcc
	v_div_scale_f32 v77, s[4:5], v18, v18, s75
	v_rcp_f32_e32 v78, v77
	v_div_scale_f32 v79, vcc, s75, v18, s75
	v_lshlrev_b32_e32 v76, 16, v86
	v_fma_f32 v80, -v77, v78, 1.0
	v_fmac_f32_e32 v78, v80, v78
	v_mul_f32_e32 v80, v79, v78
	v_fma_f32 v81, -v77, v80, v79
	v_fmac_f32_e32 v80, v81, v78
	v_fma_f32 v77, -v77, v80, v79
	v_div_fmas_f32 v77, v77, v78, v80
	v_div_fixup_f32 v18, v77, v18, s75
	v_and_b32_e32 v77, 0xffff0000, v86
	s_nop 0
	v_lshlrev_b32_e32 v78, 16, v72
	v_and_b32_e32 v79, 0xffff0000, v72
	v_pk_fma_f32 v[20:21], v[224:225], v[20:21], v[78:79] neg_lo:[1,0,0] neg_hi:[1,0,0]
	v_lshlrev_b32_e32 v72, 16, v73
	v_pk_mul_f32 v[20:21], v[18:19], v[20:21] op_sel_hi:[0,1]
	v_and_b32_e32 v73, 0xffff0000, v73
	v_lshlrev_b32_e32 v80, 16, v74
	v_and_b32_e32 v81, 0xffff0000, v74
	v_pk_mul_f32 v[20:21], v[6:7], v[20:21]
	v_pk_fma_f32 v[26:27], v[224:225], v[26:27], v[72:73] neg_lo:[1,0,0] neg_hi:[1,0,0]
	v_cvt_pk_bf16_f32 v72, v20, v21
	v_pk_fma_f32 v[20:21], v[224:225], v[76:77], v[80:81] neg_lo:[1,0,0] neg_hi:[1,0,0]
	v_pk_mul_f32 v[26:27], v[18:19], v[26:27] op_sel_hi:[0,1]
	v_pk_mul_f32 v[20:21], v[18:19], v[20:21] op_sel_hi:[0,1]
	v_pk_mul_f32 v[26:27], v[8:9], v[26:27]
	v_pk_mul_f32 v[20:21], v[2:3], v[20:21]
	v_cvt_pk_bf16_f32 v73, v26, v27
	v_cvt_pk_bf16_f32 v74, v20, v21
	v_lshlrev_b32_e32 v20, 16, v75
	v_and_b32_e32 v21, 0xffff0000, v75
	v_lshlrev_b32_e32 v26, 16, v87
	v_and_b32_e32 v27, 0xffff0000, v87
	v_pk_fma_f32 v[20:21], v[224:225], v[26:27], v[20:21] neg_lo:[1,0,0] neg_hi:[1,0,0]
	ds_bpermute_b32 v26, v241, v22
	v_pk_mul_f32 v[20:21], v[18:19], v[20:21] op_sel_hi:[0,1]
	v_pk_mul_f32 v[20:21], v[4:5], v[20:21]
	s_waitcnt lgkmcnt(0)
	v_add_f32_e32 v22, v22, v26
	v_cvt_pk_bf16_f32 v75, v20, v21
	v_lshl_add_u64 v[20:21], s[46:47], 0, v[52:53]
	v_lshlrev_b64 v[20:21], 11, v[20:21]
	v_lshl_add_u64 v[20:21], v[24:25], 0, v[20:21]
	global_store_dwordx4 v[20:21], v[72:75], off
	s_nop 1
	v_mov_b32_e32 v72, v152
	v_mov_b32_e32 v73, v153
	v_mov_b32_e32 v74, v154
	v_mov_b32_e32 v75, v155
	ds_bpermute_b32 v26, v242, v22
	ds_read_b128 v[76:79], v57
	ds_read_b128 v[84:87], v59
	s_waitcnt lgkmcnt(2)
	v_add_f32_e32 v22, v22, v26
	ds_bpermute_b32 v80, v243, v22
	s_waitcnt lgkmcnt(2)
	v_lshlrev_b32_e32 v26, 16, v76
	v_and_b32_e32 v27, 0xffff0000, v76
	v_lshlrev_b32_e32 v52, 16, v77
	v_and_b32_e32 v53, 0xffff0000, v77
	s_waitcnt lgkmcnt(0)
	v_add_f32_e32 v22, v22, v80
	v_fmamk_f32 v22, v22, 0x3c000000, v90
	v_mul_f32_e32 v76, 0x4f800000, v22
	v_cmp_gt_f32_e32 vcc, s74, v22
	v_and_b32_e32 v77, 0xffff0000, v78
	s_nop 0
	v_cndmask_b32_e32 v22, v22, v76, vcc
	v_sqrt_f32_e32 v80, v22
	v_lshlrev_b32_e32 v76, 16, v78
	v_lshlrev_b32_e32 v78, 16, v79
	v_and_b32_e32 v79, 0xffff0000, v79
	v_add_u32_e32 v81, -1, v80
	v_add_u32_e32 v83, 1, v80
	v_fma_f32 v88, -v81, v80, v22
	v_fma_f32 v89, -v83, v80, v22
	v_cmp_ge_f32_e64 s[4:5], 0, v88
	s_nop 1
	v_cndmask_b32_e64 v80, v80, v81, s[4:5]
	v_cmp_lt_f32_e64 s[4:5], 0, v89
	s_nop 1
	v_cndmask_b32_e64 v80, v80, v83, s[4:5]
	v_mul_f32_e32 v81, 0x37800000, v80
	v_cndmask_b32_e32 v80, v80, v81, vcc
	v_cmp_class_f32_e32 vcc, v22, v254
	s_nop 1
	v_cndmask_b32_e32 v22, v80, v22, vcc
	v_div_scale_f32 v80, s[4:5], v22, v22, s75
	v_rcp_f32_e32 v81, v80
	v_div_scale_f32 v83, vcc, s75, v22, s75
	v_fma_f32 v88, -v80, v81, 1.0
	v_fmac_f32_e32 v81, v88, v81
	v_mul_f32_e32 v88, v83, v81
	v_fma_f32 v89, -v80, v88, v83
	v_fmac_f32_e32 v88, v89, v81
	v_fma_f32 v80, -v80, v88, v83
	v_div_fmas_f32 v80, v80, v81, v88
	v_div_fixup_f32 v22, v80, v22, s75
	s_nop 0
	v_lshlrev_b32_e32 v80, 16, v72
	v_and_b32_e32 v81, 0xffff0000, v72
	v_lshlrev_b32_e32 v72, 16, v73
	v_and_b32_e32 v73, 0xffff0000, v73
	v_lshlrev_b32_e32 v88, 16, v74
	v_and_b32_e32 v89, 0xffff0000, v74
	v_pk_fma_f32 v[26:27], v[224:225], v[26:27], v[80:81] neg_lo:[1,0,0] neg_hi:[1,0,0]
	v_lshlrev_b32_e32 v74, 16, v75
	v_and_b32_e32 v75, 0xffff0000, v75
	v_pk_fma_f32 v[52:53], v[224:225], v[52:53], v[72:73] neg_lo:[1,0,0] neg_hi:[1,0,0]
	v_pk_fma_f32 v[72:73], v[224:225], v[76:77], v[88:89] neg_lo:[1,0,0] neg_hi:[1,0,0]
	v_pk_mul_f32 v[26:27], v[22:23], v[26:27] op_sel_hi:[0,1]
	v_pk_fma_f32 v[76:77], v[224:225], v[78:79], v[74:75] neg_lo:[1,0,0] neg_hi:[1,0,0]
	v_pk_mul_f32 v[72:73], v[22:23], v[72:73] op_sel_hi:[0,1]
	v_pk_mul_f32 v[26:27], v[6:7], v[26:27]
	v_pk_mul_f32 v[74:75], v[2:3], v[72:73]
	v_cvt_pk_bf16_f32 v72, v26, v27
	v_pk_mul_f32 v[26:27], v[22:23], v[76:77] op_sel_hi:[0,1]
	v_pk_mul_f32 v[26:27], v[4:5], v[26:27]
	v_pk_mul_f32 v[52:53], v[22:23], v[52:53] op_sel_hi:[0,1]
	v_cvt_pk_bf16_f32 v74, v74, v75
	v_cvt_pk_bf16_f32 v75, v26, v27
	v_lshl_add_u64 v[26:27], s[46:47], 0, v[50:51]
	v_pk_mul_f32 v[52:53], v[8:9], v[52:53]
	v_lshlrev_b64 v[26:27], 11, v[26:27]
	v_cvt_pk_bf16_f32 v73, v52, v53
	v_lshl_add_u64 v[26:27], v[24:25], 0, v[26:27]
	global_store_dwordx4 v[26:27], v[72:75], off
	v_mov_b32_e32 v50, v160
	v_mov_b32_e32 v51, v161
	v_mov_b32_e32 v52, v162
	v_mov_b32_e32 v53, v163
	ds_bpermute_b32 v72, v241, v28
	v_lshl_add_u64 v[24:25], v[24:25], 0, v[54:55]
	v_lshlrev_b32_e32 v54, 16, v84
	v_and_b32_e32 v55, 0xffff0000, v84
	v_and_b32_e32 v73, 0xffff0000, v85
	s_waitcnt lgkmcnt(0)
	v_add_f32_e32 v28, v28, v72
	ds_bpermute_b32 v72, v242, v28
	v_and_b32_e32 v75, 0xffff0000, v86
	v_lshlrev_b32_e32 v76, 16, v87
	s_waitcnt lgkmcnt(0)
	v_add_f32_e32 v28, v28, v72
	ds_bpermute_b32 v74, v243, v28
	v_lshlrev_b32_e32 v72, 16, v85
	s_waitcnt lgkmcnt(0)
	v_add_f32_e32 v28, v28, v74
	v_fmamk_f32 v28, v28, 0x3c000000, v90
	v_mul_f32_e32 v74, 0x4f800000, v28
	v_cmp_gt_f32_e32 vcc, s74, v28
	s_nop 1
	v_cndmask_b32_e32 v28, v28, v74, vcc
	v_sqrt_f32_e32 v77, v28
	v_lshlrev_b32_e32 v74, 16, v86
	v_add_u32_e32 v78, -1, v77
	v_add_u32_e32 v79, 1, v77
	v_fma_f32 v80, -v78, v77, v28
	v_fma_f32 v81, -v79, v77, v28
	v_cmp_ge_f32_e64 s[4:5], 0, v80
	s_nop 1
	v_cndmask_b32_e64 v77, v77, v78, s[4:5]
	v_cmp_lt_f32_e64 s[4:5], 0, v81
	s_nop 1
	v_cndmask_b32_e64 v77, v77, v79, s[4:5]
	v_mul_f32_e32 v78, 0x37800000, v77
	v_cndmask_b32_e32 v77, v77, v78, vcc
	v_cmp_class_f32_e32 vcc, v28, v254
	s_nop 1
	v_cndmask_b32_e32 v28, v77, v28, vcc
	v_div_scale_f32 v78, s[4:5], v28, v28, s75
	v_rcp_f32_e32 v79, v78
	v_div_scale_f32 v80, vcc, s75, v28, s75
	v_and_b32_e32 v77, 0xffff0000, v87
	v_fma_f32 v81, -v78, v79, 1.0
	v_fmac_f32_e32 v79, v81, v79
	v_mul_f32_e32 v81, v80, v79
	v_fma_f32 v83, -v78, v81, v80
	v_fmac_f32_e32 v81, v83, v79
	v_fma_f32 v78, -v78, v81, v80
	v_div_fmas_f32 v78, v78, v79, v81
	v_div_fixup_f32 v28, v78, v28, s75
	s_nop 0
	v_lshlrev_b32_e32 v78, 16, v50
	v_and_b32_e32 v79, 0xffff0000, v50
	v_lshlrev_b32_e32 v50, 16, v51
	v_and_b32_e32 v51, 0xffff0000, v51
	v_lshlrev_b32_e32 v80, 16, v52
	v_and_b32_e32 v81, 0xffff0000, v52
	v_lshlrev_b32_e32 v52, 16, v53
	v_and_b32_e32 v53, 0xffff0000, v53
	v_pk_fma_f32 v[54:55], v[224:225], v[54:55], v[78:79] neg_lo:[1,0,0] neg_hi:[1,0,0]
	v_pk_fma_f32 v[50:51], v[224:225], v[72:73], v[50:51] neg_lo:[1,0,0] neg_hi:[1,0,0]
	v_pk_fma_f32 v[72:73], v[224:225], v[74:75], v[80:81] neg_lo:[1,0,0] neg_hi:[1,0,0]
	v_pk_fma_f32 v[52:53], v[224:225], v[76:77], v[52:53] neg_lo:[1,0,0] neg_hi:[1,0,0]
	v_pk_mul_f32 v[54:55], v[28:29], v[54:55] op_sel_hi:[0,1]
	v_pk_mul_f32 v[50:51], v[28:29], v[50:51] op_sel_hi:[0,1]
	v_pk_mul_f32 v[72:73], v[28:29], v[72:73] op_sel_hi:[0,1]
	v_pk_mul_f32 v[52:53], v[28:29], v[52:53] op_sel_hi:[0,1]
	v_pk_mul_f32 v[6:7], v[6:7], v[54:55]
	v_pk_mul_f32 v[8:9], v[8:9], v[50:51]
	v_pk_mul_f32 v[50:51], v[2:3], v[72:73]
	v_pk_mul_f32 v[52:53], v[4:5], v[52:53]
	v_cvt_pk_bf16_f32 v2, v6, v7
	v_cvt_pk_bf16_f32 v3, v8, v9
	v_cvt_pk_bf16_f32 v4, v50, v51
	v_cvt_pk_bf16_f32 v5, v52, v53
	global_store_dwordx4 v[24:25], v[2:5], off
	s_waitcnt lgkmcnt(0)
	ds_write_b16 v82, v32
	ds_write_b16 v82, v60 offset:64
	ds_write_b16 v82, v33 offset:128
	ds_write_b16 v82, v61 offset:192
	ds_write_b16 v82, v34 offset:256
	ds_write_b16 v82, v62 offset:320
	ds_write_b16 v82, v35 offset:384
	ds_write_b16 v82, v19 offset:448
	ds_write_b16 v82, v36 offset:1024
	ds_write_b16 v82, v63 offset:1088
	ds_write_b16 v82, v37 offset:1152
	ds_write_b16 v82, v64 offset:1216
	ds_write_b16 v82, v38 offset:1280
	ds_write_b16 v82, v65 offset:1344
	ds_write_b16 v82, v39 offset:1408
	ds_write_b16 v82, v23 offset:1472
	ds_write_b16 v82, v40 offset:2048
	ds_write_b16 v82, v66 offset:2112
	ds_write_b16 v82, v41 offset:2176
	ds_write_b16 v82, v67 offset:2240
	ds_write_b16 v82, v42 offset:2304
	ds_write_b16 v82, v68 offset:2368
	ds_write_b16 v82, v43 offset:2432
	ds_write_b16 v82, v69 offset:2496
	ds_write_b16 v82, v44 offset:3072
	ds_write_b16 v82, v70 offset:3136
	ds_write_b16 v82, v45 offset:3200
	ds_write_b16 v82, v29 offset:3264
	ds_write_b16 v82, v46 offset:3328
	ds_write_b16 v82, v30 offset:3392
	ds_write_b16 v82, v47 offset:3456
	ds_write_b16 v82, v31 offset:3520
	s_waitcnt lgkmcnt(0)
	v_mov_b32_e32 v30, v140
	v_mov_b32_e32 v31, v141
	v_mov_b32_e32 v32, v142
	v_mov_b32_e32 v33, v143
	global_load_dwordx4 v[6:9], v71, s[8:9] offset:256
	global_load_dwordx4 v[2:5], v71, s[8:9] offset:272
	ds_read_b128 v[34:37], v56
	ds_read_b128 v[38:41], v58
	s_waitcnt lgkmcnt(1)
	v_lshlrev_b32_e32 v10, 16, v34
	v_and_b32_e32 v11, 0xffff0000, v34
	v_lshlrev_b32_e32 v34, 16, v35
	v_and_b32_e32 v35, 0xffff0000, v35
	v_lshlrev_b32_e32 v42, 16, v36
	v_and_b32_e32 v43, 0xffff0000, v36
	v_lshlrev_b32_e32 v36, 16, v37
	v_and_b32_e32 v37, 0xffff0000, v37
	s_waitcnt vmcnt(2)
	v_lshlrev_b32_e32 v44, 16, v30
	v_and_b32_e32 v45, 0xffff0000, v30
	v_lshlrev_b32_e32 v30, 16, v31
	v_and_b32_e32 v31, 0xffff0000, v31
	v_lshlrev_b32_e32 v46, 16, v32
	v_and_b32_e32 v47, 0xffff0000, v32
	v_lshlrev_b32_e32 v32, 16, v33
	v_and_b32_e32 v33, 0xffff0000, v33
	v_pk_fma_f32 v[10:11], v[224:225], v[10:11], v[44:45] neg_lo:[1,0,0] neg_hi:[1,0,0]
	v_pk_fma_f32 v[30:31], v[224:225], v[34:35], v[30:31] neg_lo:[1,0,0] neg_hi:[1,0,0]
	v_pk_fma_f32 v[34:35], v[224:225], v[42:43], v[46:47] neg_lo:[1,0,0] neg_hi:[1,0,0]
	v_pk_fma_f32 v[32:33], v[224:225], v[36:37], v[32:33] neg_lo:[1,0,0] neg_hi:[1,0,0]
	v_pk_mul_f32 v[10:11], v[0:1], v[10:11] op_sel_hi:[0,1]
	v_pk_mul_f32 v[30:31], v[0:1], v[30:31] op_sel_hi:[0,1]
	v_pk_mul_f32 v[34:35], v[0:1], v[34:35] op_sel_hi:[0,1]
	v_pk_mul_f32 v[32:33], v[0:1], v[32:33] op_sel_hi:[0,1]
	s_waitcnt vmcnt(1)
	v_pk_mul_f32 v[10:11], v[6:7], v[10:11]
	v_pk_mul_f32 v[36:37], v[8:9], v[30:31]
	s_waitcnt vmcnt(0)
	v_pk_mul_f32 v[34:35], v[2:3], v[34:35]
	v_pk_mul_f32 v[42:43], v[32:33], v[4:5]
	v_cvt_pk_bf16_f32 v30, v10, v11
	v_cvt_pk_bf16_f32 v31, v36, v37
	v_cvt_pk_bf16_f32 v32, v34, v35
	v_cvt_pk_bf16_f32 v33, v42, v43
	global_store_dwordx4 v[16:17], v[30:33], off offset:128
	v_mov_b32_e32 v10, v148
	v_mov_b32_e32 v11, v149
	v_mov_b32_e32 v12, v150
	v_mov_b32_e32 v13, v151
	s_waitcnt lgkmcnt(0)
	v_lshlrev_b32_e32 v16, 16, v38
	v_and_b32_e32 v17, 0xffff0000, v38
	v_lshlrev_b32_e32 v30, 16, v39
	v_and_b32_e32 v31, 0xffff0000, v39
	v_lshlrev_b32_e32 v32, 16, v40
	v_and_b32_e32 v33, 0xffff0000, v40
	v_lshlrev_b32_e32 v34, 16, v41
	v_and_b32_e32 v35, 0xffff0000, v41
	s_nop 0
	v_lshlrev_b32_e32 v36, 16, v10
	v_and_b32_e32 v37, 0xffff0000, v10
	v_lshlrev_b32_e32 v10, 16, v11
	v_and_b32_e32 v11, 0xffff0000, v11
	v_lshlrev_b32_e32 v38, 16, v12
	v_and_b32_e32 v39, 0xffff0000, v12
	v_lshlrev_b32_e32 v12, 16, v13
	v_and_b32_e32 v13, 0xffff0000, v13
	v_pk_fma_f32 v[16:17], v[224:225], v[16:17], v[36:37] neg_lo:[1,0,0] neg_hi:[1,0,0]
	v_pk_fma_f32 v[10:11], v[224:225], v[30:31], v[10:11] neg_lo:[1,0,0] neg_hi:[1,0,0]
	v_pk_fma_f32 v[30:31], v[224:225], v[32:33], v[38:39] neg_lo:[1,0,0] neg_hi:[1,0,0]
	v_pk_fma_f32 v[12:13], v[224:225], v[34:35], v[12:13] neg_lo:[1,0,0] neg_hi:[1,0,0]
	v_pk_mul_f32 v[16:17], v[18:19], v[16:17] op_sel_hi:[0,1]
	v_pk_mul_f32 v[10:11], v[18:19], v[10:11] op_sel_hi:[0,1]
	v_pk_mul_f32 v[30:31], v[18:19], v[30:31] op_sel_hi:[0,1]
	v_pk_mul_f32 v[12:13], v[18:19], v[12:13] op_sel_hi:[0,1]
	v_pk_mul_f32 v[16:17], v[6:7], v[16:17]
	v_pk_mul_f32 v[18:19], v[8:9], v[10:11]
	v_pk_mul_f32 v[30:31], v[2:3], v[30:31]
	v_pk_mul_f32 v[32:33], v[4:5], v[12:13]
	v_cvt_pk_bf16_f32 v10, v16, v17
	v_cvt_pk_bf16_f32 v11, v18, v19
	v_cvt_pk_bf16_f32 v12, v30, v31
	v_cvt_pk_bf16_f32 v13, v32, v33
	global_store_dwordx4 v[20:21], v[10:13], off offset:128
	s_nop 1
	v_mov_b32_e32 v10, v156
	v_mov_b32_e32 v11, v157
	v_mov_b32_e32 v12, v158
	v_mov_b32_e32 v13, v159
	ds_read_b128 v[14:17], v57
	ds_read_b128 v[18:21], v59
	s_waitcnt lgkmcnt(1)
	v_lshlrev_b32_e32 v30, 16, v14
	v_and_b32_e32 v31, 0xffff0000, v14
	v_lshlrev_b32_e32 v14, 16, v15
	v_and_b32_e32 v15, 0xffff0000, v15
	v_lshlrev_b32_e32 v32, 16, v16
	v_and_b32_e32 v33, 0xffff0000, v16
	v_lshlrev_b32_e32 v16, 16, v17
	v_and_b32_e32 v17, 0xffff0000, v17
	s_nop 0
	v_lshlrev_b32_e32 v34, 16, v10
	v_and_b32_e32 v35, 0xffff0000, v10
	v_lshlrev_b32_e32 v10, 16, v11
	v_and_b32_e32 v11, 0xffff0000, v11
	v_lshlrev_b32_e32 v36, 16, v12
	v_and_b32_e32 v37, 0xffff0000, v12
	v_lshlrev_b32_e32 v12, 16, v13
	v_and_b32_e32 v13, 0xffff0000, v13
	v_pk_fma_f32 v[30:31], v[224:225], v[30:31], v[34:35] neg_lo:[1,0,0] neg_hi:[1,0,0]
	v_pk_fma_f32 v[10:11], v[224:225], v[14:15], v[10:11] neg_lo:[1,0,0] neg_hi:[1,0,0]
	v_pk_fma_f32 v[14:15], v[224:225], v[32:33], v[36:37] neg_lo:[1,0,0] neg_hi:[1,0,0]
	v_pk_fma_f32 v[12:13], v[224:225], v[16:17], v[12:13] neg_lo:[1,0,0] neg_hi:[1,0,0]
	v_pk_mul_f32 v[16:17], v[22:23], v[30:31] op_sel_hi:[0,1]
	v_pk_mul_f32 v[10:11], v[22:23], v[10:11] op_sel_hi:[0,1]
	v_pk_mul_f32 v[14:15], v[22:23], v[14:15] op_sel_hi:[0,1]
	v_pk_mul_f32 v[12:13], v[22:23], v[12:13] op_sel_hi:[0,1]
	v_pk_mul_f32 v[16:17], v[6:7], v[16:17]
	v_pk_mul_f32 v[22:23], v[8:9], v[10:11]
	v_pk_mul_f32 v[14:15], v[2:3], v[14:15]
	v_pk_mul_f32 v[30:31], v[4:5], v[12:13]
	v_cvt_pk_bf16_f32 v10, v16, v17
	v_cvt_pk_bf16_f32 v11, v22, v23
	v_cvt_pk_bf16_f32 v12, v14, v15
	v_cvt_pk_bf16_f32 v13, v30, v31
	global_store_dwordx4 v[26:27], v[10:13], off offset:128
	s_nop 1
	v_mov_b32_e32 v10, v164
	v_mov_b32_e32 v11, v165
	v_mov_b32_e32 v12, v166
	v_mov_b32_e32 v13, v167
	s_waitcnt lgkmcnt(0)
	v_lshlrev_b32_e32 v14, 16, v18
	v_and_b32_e32 v15, 0xffff0000, v18
	v_lshlrev_b32_e32 v16, 16, v19
	v_and_b32_e32 v17, 0xffff0000, v19
	v_lshlrev_b32_e32 v18, 16, v20
	v_and_b32_e32 v19, 0xffff0000, v20
	v_lshlrev_b32_e32 v20, 16, v21
	v_and_b32_e32 v21, 0xffff0000, v21
	s_nop 0
	v_lshlrev_b32_e32 v22, 16, v10
	v_and_b32_e32 v23, 0xffff0000, v10
	v_lshlrev_b32_e32 v10, 16, v11
	v_and_b32_e32 v11, 0xffff0000, v11
	v_lshlrev_b32_e32 v26, 16, v12
	v_and_b32_e32 v27, 0xffff0000, v12
	v_lshlrev_b32_e32 v12, 16, v13
	v_and_b32_e32 v13, 0xffff0000, v13
	v_pk_fma_f32 v[14:15], v[224:225], v[14:15], v[22:23] neg_lo:[1,0,0] neg_hi:[1,0,0]
	v_pk_fma_f32 v[10:11], v[224:225], v[16:17], v[10:11] neg_lo:[1,0,0] neg_hi:[1,0,0]
	v_pk_fma_f32 v[16:17], v[224:225], v[18:19], v[26:27] neg_lo:[1,0,0] neg_hi:[1,0,0]
	v_pk_fma_f32 v[12:13], v[224:225], v[20:21], v[12:13] neg_lo:[1,0,0] neg_hi:[1,0,0]
	v_pk_mul_f32 v[14:15], v[28:29], v[14:15] op_sel_hi:[0,1]
	v_pk_mul_f32 v[10:11], v[28:29], v[10:11] op_sel_hi:[0,1]
	v_pk_mul_f32 v[16:17], v[28:29], v[16:17] op_sel_hi:[0,1]
	v_pk_mul_f32 v[12:13], v[28:29], v[12:13] op_sel_hi:[0,1]
	v_pk_mul_f32 v[6:7], v[6:7], v[14:15]
	v_pk_mul_f32 v[8:9], v[8:9], v[10:11]
	v_pk_mul_f32 v[10:11], v[2:3], v[16:17]
	v_pk_mul_f32 v[12:13], v[4:5], v[12:13]
	v_cvt_pk_bf16_f32 v2, v6, v7
	v_cvt_pk_bf16_f32 v3, v8, v9
	v_cvt_pk_bf16_f32 v4, v10, v11
	v_cvt_pk_bf16_f32 v5, v12, v13
	global_store_dwordx4 v[24:25], v[2:5], off offset:128
	s_waitcnt lgkmcnt(0)
	s_branch .LBB0_894
